# stagger-24 stack + prompt-first workgroups start the mixer 48x64 clocks late so the queue-first half's sample items load their K/V caches first
# speedup vs baseline: 1.0028x; 1.0028x over previous
; #define LAS __attribute__((address_space(3)))
; __device__ __forceinline__ void attn_prompt_item(const Args& a, int l, int item, LAS unsigned char* lds, int tid, int lane, int wave) {
;     const int kvh = item & 1, b = (item >> 1) & 31, n = item >> 6;
;     const bf16_t* proj = (const bf16_t*)(a.ws + WS_PROJ); bf16_t* Y = (bf16_t*)(a.ws + WS_H);
;     const float* tab = (const float*)(a.ws + WS_ROPE);
;     const float* kg = a.in[13] + l * 64; const float* qg = a.in[12] + l * 64; const float* sinks = a.in[14] + l * 8;
;     LAS unsigned char* Kl = lds; LAS unsigned char* Vl = lds + 36864; LAS float* wsf = (LAS float*)(lds + 36864 + 32768) + wave * 64; LAS bf16_t* ost = (LAS bf16_t*)(lds + 73728 + wave * 4096);
;     const int headw = kvh * 4 + (wave >> 1), qt0 = (wave & 1) * 2, rowq0 = n * LP + b * 128 + qt0 * 32;
; __device__ __forceinline__ void p_mixer(const Args& a, int l, LAS unsigned char* lds, int tid, int lane, int wave, int bid, int G) {
;     constexpr int N_AP = NPB * 32 * 2, N_AS = NSB, N_CV = M / 64;
;     unsigned* head = (unsigned*)(a.ws + WS_BAR) + QUEUE_WORD + 64 * l;
;     volatile LAS unsigned* slot = (volatile LAS unsigned*)(lds + 131072 + 128);
;     const bool qfirst = ((bid >> 3) & 1) != 0;
;     bool prompt_done = false, queue_empty = false; int pulled = 0;
.LBB0_439:
	s_or_b64 exec, exec, s[0:1]
	v_mov_b32_e32 v130, v208
	s_waitcnt lgkmcnt(0)
	s_barrier
	s_cmp_lg_u32 s42, 0x100
	s_cbranch_scc1 .Lmsl_skip
	s_bitcmp1_b32 s71, 3
	s_cbranch_scc1 .Lmsl_skip
	s_sleep 48
.Lmsl_skip:
	s_lshl_b32 s86, s66, 6
	v_readfirstlane_b32 s2, v130
	s_ashr_i32 s6, s2, 6
	s_lshl_b64 s[0:1], s[86:87], 2
	v_readlane_b32 s3, v254, 8
	s_add_u32 s4, s3, s0
	v_readlane_b32 s3, v254, 9
	s_addc_u32 s5, s3, s1
	v_writelane_b32 v255, s4, 15
	s_ashr_i32 s45, s2, 7
	s_lshl_b32 s2, s6, 1
	v_writelane_b32 v255, s5, 16
	s_and_b32 s2, s2, 2
	s_lshl_b32 s4, s6, 12
	s_add_i32 s7, s4, 0
	s_mul_i32 s4, s2, 0x1200
	s_lshl_b32 s33, s2, 5
	s_add_i32 s85, s4, 0
	s_mul_i32 s4, s2, 0xfffff600
	s_sub_i32 s61, 4, s2
	s_xor_b32 s83, s2, 3
	s_lshl_b32 s2, s6, 3
	s_lshl_b32 s10, s6, 8
	s_addk_i32 s2, 0xe000
	s_add_i32 s8, s10, 0
	v_writelane_b32 v255, s2, 17
	s_lshl_b32 s2, s66, 8
	s_add_i32 s60, s85, s4
	s_or_b32 s4, s33, 32
	v_writelane_b32 v255, s2, 18
	s_add_i32 s2, s8, 0x18000
	s_mul_i32 s5, s4, 0x90
	v_writelane_b32 v255, s2, 19
	s_add_i32 s2, s7, 0x19000
	s_add_i32 s82, s5, 0
	s_mulk_i32 s4, 0xffb0
	v_writelane_b32 v255, s2, 20
	s_lshl_b32 s72, s66, 2
	s_add_i32 s64, s7, 0x12000
	s_add_i32 s65, s8, 0x11000
	s_lshl_b32 s86, s66, 3
	s_add_i32 s70, s82, s4
	s_mul_i32 s4, s66, 0x600
	v_writelane_b32 v255, s66, 21
	s_lshl_b32 s2, s66, 7
	s_cmp_lt_i32 s6, 2
	v_writelane_b32 v255, s67, 22
	v_writelane_b32 v255, s2, 23
	s_cselect_b64 s[2:3], -1, 0
	v_writelane_b32 v255, s2, 24
	s_ashr_i32 s11, s10, 31
	s_mov_b32 s5, s87
	v_writelane_b32 v255, s3, 25
	v_writelane_b32 v255, s10, 26
	s_mul_i32 s2, s6, 0x5a00
	s_add_i32 s3, s2, 0
	v_writelane_b32 v255, s11, 27
	v_readlane_b32 s8, v253, 20
	s_mul_i32 s2, s6, 0xfffff600
	v_readlane_b32 s10, v253, 22
	v_readlane_b32 s11, v253, 23
	v_readlane_b32 s12, v253, 24
	v_readlane_b32 s13, v253, 25
	v_readlane_b32 s14, v253, 26
	v_readlane_b32 s15, v253, 27
	v_readlane_b32 s16, v253, 28
	v_readlane_b32 s17, v253, 29
	v_writelane_b32 v255, s3, 28
	s_add_i32 s2, s3, s2
	v_readlane_b32 s18, v253, 30
	v_readlane_b32 s19, v253, 31
	v_readlane_b32 s20, v253, 32
	v_readlane_b32 s21, v253, 33
	s_mov_b64 s[10:11], s[14:15]
	s_mov_b64 s[12:13], s[16:17]
	v_writelane_b32 v255, s2, 29
	s_lshl_b32 s2, s6, 2
	s_mov_b64 s[14:15], s[18:19]
	s_add_u32 s98, s14, s0
	s_mov_b64 s[16:17], s[20:21]
	s_addc_u32 s99, s15, s1
	s_lshl_b64 s[6:7], s[86:87], 2
	s_add_u32 s80, s16, s6
	s_addc_u32 s81, s17, s7
	s_add_u32 s62, s12, s0
	s_addc_u32 s63, s13, s1
	s_lshl_b64 s[0:1], s[4:5], 2
	s_add_u32 s0, s10, s0
	v_writelane_b32 v255, s2, 30
	s_addc_u32 s1, s11, s1
	v_writelane_b32 v255, s0, 31
	s_mov_b32 s93, 0
	s_mov_b64 s[68:69], 0
	v_writelane_b32 v255, s1, 32
	s_mov_b64 s[66:67], 0
	v_readlane_b32 s9, v253, 21
	v_readlane_b32 s22, v253, 34
	v_readlane_b32 s23, v253, 35
	s_branch .LBB0_441
